# chunkB loop: saddr next-chunk loads spread over the step, Q as dwordx4, invariant ln/mu loads hoisted, prefetch waited at rotation
# speedup vs baseline: 1.0380x; 1.0077x over previous
; #define LAS __attribute__((address_space(3)))
; __device__ __forceinline__ float sigmoidf_(float x) { return __builtin_amdgcn_rcpf(1.f + __expf(-x)); }
; __device__ __forceinline__ void chunkA_item(const Args& A, LAS unsigned char* lds, int tid, int lane, int wave, int ci, int ci_next, HeadConstA& H) {
;     ...
;         const int mt = wave & 3, nth = wave >> 2;
;         bf16x8 ath[2], aad[2];
; #pragma unroll
;         for (int ks = 0; ks < 2; ++ks) { ath[ks] = ldsfrag(lds + CA_TH, mt * 16 + fr, ks * 32 + q4 * 8); aad[ks] = ldsfrag(lds + CA_AD, mt * 16 + fr, ks * 32 + q4 * 8); }
; #pragma unroll
;         for (int nn = 0; nn < 2; ++nn) {
;             const int cl = (nth * 2 + nn) * 16 + fr;
;             f32x4 accw = {0.f, 0.f, 0.f, 0.f}, acca = {0.f, 0.f, 0.f, 0.f};
; #pragma unroll
;             for (int ks = 0; ks < 2; ++ks) { accw = MFMA16(ath[ks], H.bw[nn][ks], accw); acca = MFMA16(aad[ks], H.ba[nn][ks], acca); }
;             const float w0c = H.w0c[nn], a0c = H.a0c[nn];
; #pragma unroll
;             for (int jj = 0; jj < 4; ++jj) { const int t = mt * 16 + q4 * 4 + jj;
;                 ((LAS float*)(lds + CA_LW))[t * 64 + cl] = -0.6065306597126334f * sigmoidf_(w0c + accw[jj]);
;                 ((LAS float*)(lds + CA_AA))[t * 64 + cl] = sigmoidf_(a0c + acca[jj]); }
;         }
;     }
;     LBAR();
;     {
;         const int cc = lane, seg = wave;
;         float lwv[8], pre[8], zr[8], zk[8], zv[8], av[8];
; #pragma unroll
;         for (int i = 0; i < 8; ++i) { const int t = seg * 8 + i; lwv[i] = ((LAS float*)(lds + CA_LW))[t * 64 + cc]; zr[i] = ((LAS float*)(lds + CA_ZR))[t * 64 + cc];
;             zk[i] = ((LAS float*)(lds + CA_ZK))[t * 64 + cc]; zv[i] = ((LAS float*)(lds + CA_ZV))[t * 64 + cc]; av[i] = ((LAS float*)(lds + CA_AA))[t * 64 + cc]; }
;         pre[0] = lwv[0];
; #pragma unroll
;         for (int i = 1; i < 8; ++i) pre[i] = pre[i - 1] + lwv[i];
;         ((LAS float*)(lds + CA_SEG))[seg * 64 + cc] = pre[7];
;         LBAR();
;         float off = 0.f, tot = 0.f;
; #pragma unroll
;         for (int s = 0; s < 8; ++s) { const float v = ((LAS float*)(lds + CA_SEG))[s * 64 + cc]; tot += v; if (s < seg) off += v; }
;         const float kkc = H.kkc, kac = H.kac, rkc = H.rkc;
;         float rhs8[8], nbh8[8], kh8[8];
;         float* BCg = (float*)(A.ws + WS_BC) + (size_t)ci * 64;
.LBB0_143:
	s_or_b64 exec, exec, s[4:5]
	s_add_u32 s4, s96, 0xd80000
	s_addc_u32 s5, s97, 0
	v_writelane_b32 v249, s4, 32
	v_lshrrev_b32_e32 v0, 2, v144
	v_lshlrev_b32_e32 v137, 2, v145
	v_writelane_b32 v249, s5, 33
	s_add_u32 s4, s96, 0xda0000
	s_addc_u32 s5, s97, 0
	v_writelane_b32 v249, s4, 34
	s_cmpk_gt_i32 s2, 0xfff
	v_and_b32_e32 v89, 48, v144
	v_cmp_eq_u32_e64 s[82:83], 0, v145
	v_or_b32_e32 v88, 48, v145
	v_writelane_b32 v249, s5, 35
	s_barrier
	s_cbranch_scc1 .LBB0_261
	v_mov_b32_e32 v73, 0
	v_readlane_b32 s4, v249, 32
	s_add_i32 s3, 0, 0x18800
	v_mov_b32_e32 v135, v73
	v_readlane_b32 s5, v249, 33
	v_readlane_b32 s10, v249, 3
	v_add_u32_e32 v79, s3, v137
	v_lshl_add_u64 v[74:75], s[4:5], 0, v[134:135]
	v_readlane_b32 s4, v249, 34
	s_lshl_b32 s3, s10, 3
	v_readlane_b32 s5, v249, 35
	s_and_b32 s91, s3, 0x1fffffe0
	v_lshlrev_b32_e32 v2, 5, v207
	v_lshl_add_u64 v[76:77], s[4:5], 0, v[134:135]
	s_or_b32 s4, s91, 16
	v_writelane_b32 v249, s4, 36
	v_or_b32_e32 v72, 0x1800, v2
	v_readlane_b32 s56, v249, 0
	s_bfe_u32 s13, s56, 0x20006
	s_lshl_b32 s5, s13, 4
	s_movk_i32 s4, 0x90
	v_lshl_add_u64 v[80:81], s[60:61], 0, v[72:73]
	v_or_b32_e32 v72, 0x1900, v2
	v_or_b32_e32 v2, s5, v132
	v_mad_u32_u24 v5, v2, s4, 0
	v_lshrrev_b32_e32 v2, 2, v145
	v_and_b32_e32 v2, 12, v2
	s_lshr_b32 s18, s56, 8
	v_or_b32_e32 v12, s5, v2
	v_lshl_or_b32 v6, s18, 5, v132
	v_lshlrev_b32_e32 v7, 6, v12
	v_add_lshl_u32 v8, v7, v6, 2
	s_add_i32 s6, 0, 0x10800
	s_add_i32 s7, 0, 0x14800
	v_add_u32_e32 v114, s6, v8
	v_add_u32_e32 v115, s7, v8
	v_or_b32_e32 v8, 64, v7
	v_add_lshl_u32 v9, v8, v6, 2
	v_add_u32_e32 v116, s6, v9
	v_add_u32_e32 v117, s7, v9
	v_or_b32_e32 v9, 0x80, v7
	v_add_lshl_u32 v10, v9, v6, 2
	v_add_u32_e32 v118, s6, v10
	v_add_u32_e32 v119, s7, v10
	v_or_b32_e32 v10, 0xc0, v7
	v_add_lshl_u32 v11, v10, v6, 2
	v_or_b32_e32 v6, 16, v6
	v_add_lshl_u32 v7, v7, v6, 2
	v_add_u32_e32 v122, s6, v7
	v_add_u32_e32 v123, s7, v7
	v_add_lshl_u32 v7, v8, v6, 2
	v_add_u32_e32 v124, s6, v7
	v_add_u32_e32 v125, s7, v7
	v_add_lshl_u32 v7, v9, v6, 2
	v_add_lshl_u32 v6, v10, v6, 2
	v_add_u32_e32 v135, s6, v6
	v_add_u32_e32 v139, s7, v6
	v_lshl_or_b32 v6, s10, 11, v137
	v_add_u32_e32 v126, s6, v7
	v_add_u32_e32 v127, s7, v7
	v_or_b32_e32 v7, 0x100, v6
	v_add_u32_e32 v149, s6, v7
	v_add_u32_e32 v150, s7, v7
	v_or_b32_e32 v7, 0x200, v6
	v_add_u32_e32 v151, s6, v7
	v_add_u32_e32 v152, s7, v7
	v_or_b32_e32 v7, 0x300, v6
	v_add_u32_e32 v153, s6, v7
	v_add_u32_e32 v154, s7, v7
	v_or_b32_e32 v7, 0x400, v6
	v_add_u32_e32 v155, s6, v7
	v_add_u32_e32 v156, s7, v7
	v_or_b32_e32 v7, 0x500, v6
	v_add_u32_e32 v141, s6, v6
	v_add_u32_e32 v143, 0, v6
	v_add_u32_e32 v148, s7, v6
	v_add_u32_e32 v157, s6, v7
	v_add_u32_e32 v158, s7, v7
	v_or_b32_e32 v7, 0x600, v6
	v_or_b32_e32 v6, 0x700, v6
	v_add_u32_e32 v120, s6, v11
	v_add_u32_e32 v159, s6, v7
	v_add_u32_e32 v161, s6, v6
	s_lshl_b32 s6, s10, 8
	s_cmp_lt_u32 s56, 64
	s_cselect_b64 s[14:15], -1, 0
	s_cmpk_gt_u32 s56, 0x7f
	v_add_u32_e32 v121, s7, v11
	v_add_u32_e32 v160, s7, v7
	v_add_u32_e32 v163, s7, v6
	v_writelane_b32 v249, s6, 37
	s_cselect_b64 s[6:7], -1, 0
	v_writelane_b32 v249, s6, 38
	s_cmpk_gt_u32 s56, 0xbf
	s_mov_b32 s11, 0x1d100
	v_writelane_b32 v249, s7, 39
	s_cselect_b64 s[6:7], -1, 0
	s_cmpk_gt_u32 s56, 0xff
	v_writelane_b32 v249, s6, 40
	s_cselect_b64 s[8:9], -1, 0
	s_cmpk_gt_u32 s56, 0x13f
	v_writelane_b32 v249, s7, 41
	s_cselect_b64 s[6:7], -1, 0
	v_writelane_b32 v249, s6, 42
	s_cmpk_gt_u32 s56, 0x17f
	v_lshlrev_b32_e32 v9, 1, v12
	v_writelane_b32 v249, s7, 43
	s_cselect_b64 s[6:7], -1, 0
	v_writelane_b32 v249, s6, 44
	s_cmpk_gt_u32 s56, 0x1bf
	v_cmp_le_u32_e64 s[20:21], v12, v132
	v_writelane_b32 v249, s7, 45
	s_cselect_b64 s[6:7], -1, 0
	v_writelane_b32 v249, s6, 46
	s_cmpk_gt_u32 s56, 0x1ff
	v_cndmask_b32_e64 v10, 0, 1, s[20:21]
	v_writelane_b32 v249, s7, 47
	s_cselect_b64 s[6:7], -1, 0
	v_writelane_b32 v249, s6, 48
	v_cmp_le_u32_e64 s[46:47], v12, v88
	s_movk_i32 s5, 0x100
	v_writelane_b32 v249, s7, 49
	s_add_u32 s6, s96, 0x1cb00000
	v_writelane_b32 v249, s6, 50
	s_addc_u32 s6, s97, 0
	v_writelane_b32 v249, s6, 51
	s_or_b32 s6, s3, 1
	s_mulk_i32 s6, 0x90
	s_lshl_b32 s12, s10, 5
	v_writelane_b32 v249, s6, 52
	s_lshl_b32 s79, s10, 4
	s_add_i32 s78, s12, 0
	s_add_i32 s6, 0, 0x19000
	s_cmpk_lt_u32 s56, 0x100
	s_cselect_b64 s[50:51], -1, 0
	s_and_b64 s[16:17], s[50:51], exec
	s_cselect_b32 s7, 0, 0x6c00
	s_cselect_b32 s11, s11, 0x21900
	s_add_i32 s7, s7, 0
	s_add_i32 s16, s11, 0
	s_add_i32 s11, 0, 0x19100
	s_add_i32 s17, s11, s79
	v_add_u32_e32 v166, s7, v89
	s_add_i32 s7, 0, 0x1f500
	s_cmp_eq_u32 s18, 1
	v_add_u32_e32 v7, s17, v2
	v_add_u32_e32 v167, s16, v9
	s_cselect_b64 s[16:17], -1, 0
	v_cmp_lt_u32_e64 s[18:19], v12, v132
	v_add_u32_e32 v168, s7, v9
	v_writelane_b32 v249, s16, 53
	s_cmp_lg_u32 s13, 0
	v_cndmask_b32_e64 v9, 0, 1, s[18:19]
	v_writelane_b32 v249, s17, 54
	s_cselect_b64 s[16:17], -1, 0
	v_cndmask_b32_e64 v9, v10, v9, s[50:51]
	v_writelane_b32 v249, s16, 55
	v_and_b32_e32 v9, 1, v9
	v_cndmask_b32_e64 v10, 0, 1, s[50:51]
	v_writelane_b32 v249, s17, 56
	v_cmp_eq_u32_e64 s[16:17], 1, v9
	v_or_b32_e32 v9, v2, v10
	s_cmp_lt_u32 s13, 2
	v_writelane_b32 v249, s16, 57
	v_add_u32_e32 v171, 0, v89
	s_movk_i32 s10, 0x110
	v_writelane_b32 v249, s17, 58
	v_cmp_gt_u32_e64 s[16:17], v132, v9
	v_or_b32_e32 v9, 2, v2
	v_cmp_lt_u32_e64 s[22:23], v9, v132
	v_cmp_le_u32_e64 s[24:25], v9, v132
	v_writelane_b32 v249, s16, 59
	v_cndmask_b32_e64 v9, 0, 1, s[22:23]
	v_cndmask_b32_e64 v11, 0, 1, s[24:25]
	v_cndmask_b32_e64 v9, v11, v9, s[50:51]
	v_and_b32_e32 v9, 1, v9
	v_writelane_b32 v249, s17, 60
	v_cmp_eq_u32_e64 s[16:17], 1, v9
; #define LAS __attribute__((address_space(3)))
; __device__ __forceinline__ u32x2 pack4(float a, float b, float c, float d) { u32x2 o; o.x = pk2(a, b); o.y = pk2(c, d); return o; }
; #define MFMA16(a, b, c) __builtin_amdgcn_mfma_f32_16x16x32_bf16(a, b, c, 0, 0, 0)
; __device__ __forceinline__ void chunkA_item(const Args& A, LAS unsigned char* lds, int tid, int lane, int wave, int ci, int ci_next, HeadConstA& H) {
;     ...
;         for (int nt = 0; nt < 4; ++nt) {
;             const int t = nt * 16 + fr, s0 = ms * 16 + q4 * 4;
;             if (nt < ms) {
;                 *(LAS u32x2*)(O1 + t * 144 + s0 * 2) = (u32x2){0u, 0u};
;                 if (og == 1) *(LAS u32x2*)(lds + CA_NMRB + t * 144 + s0 * 2) = (u32x2){0u, 0u};
;             } else {
;                 f32x4 acc1 = {0.f, 0.f, 0.f, 0.f}, acc2 = {0.f, 0.f, 0.f, 0.f};
; #pragma unroll
;                 for (int ks = 0; ks < 2; ++ks) { const bf16x8 bb = ldsfrag(Bsrc, t, ks * 32 + q4 * 8); acc1 = MFMA16(aB[ks], bb, acc1); acc2 = MFMA16(aK[ks], bb, acc2); }
;                 float v1[4], v2[4];
; #pragma unroll
;                 for (int jj = 0; jj < 4; ++jj) { const int s = s0 + jj; const bool ok = og == 0 ? (s < t) : (s <= t); v1[jj] = ok ? acc1[jj] : 0.f; v2[jj] = ok ? acc2[jj] : 0.f; }
;                 *(LAS u32x2*)(O1 + t * 144 + s0 * 2) = pack4(v2[0], v2[1], v2[2], v2[3]);
;                 if (og == 0) {
; #pragma unroll
;                     for (int jj = 0; jj < 4; ++jj) ((LAS float*)(lds + CA_N))[t * 64 + jj * 16 + ms * 4 + q4] = v1[jj];
;                 } else *(LAS u32x2*)(lds + CA_NMRB + t * 144 + s0 * 2) = pack4(-v1[0], -v1[1], -v1[2], -v1[3]);
;             }
	v_or_b32_e32 v9, 3, v2
	v_cmp_lt_u32_e64 s[24:25], v9, v132
	v_cmp_le_u32_e64 s[26:27], v9, v132
	v_writelane_b32 v249, s16, 61
	v_cndmask_b32_e64 v9, 0, 1, s[24:25]
	v_cndmask_b32_e64 v11, 0, 1, s[26:27]
	v_cndmask_b32_e64 v9, v11, v9, s[50:51]
	v_and_b32_e32 v9, 1, v9
	v_or_b32_e32 v11, 16, v132
	v_writelane_b32 v249, s17, 62
	v_cmp_eq_u32_e64 s[16:17], 1, v9
	v_cmp_lt_u32_e64 s[26:27], v12, v11
	v_cmp_le_u32_e64 s[28:29], v12, v11
	v_writelane_b32 v249, s16, 63
	v_cndmask_b32_e64 v13, 0, 1, s[26:27]
	v_cndmask_b32_e64 v14, 0, 1, s[28:29]
	v_writelane_b32 v248, s17, 0
	s_cselect_b64 s[16:17], -1, 0
	v_cndmask_b32_e64 v13, v14, v13, s[50:51]
	v_writelane_b32 v248, s16, 1
	v_and_b32_e32 v13, 1, v13
	v_or_b32_e32 v14, 2, v12
	v_writelane_b32 v248, s17, 2
	v_cmp_eq_u32_e64 s[16:17], 1, v13
	v_cmp_lt_u32_e64 s[30:31], v14, v11
	v_cmp_le_u32_e64 s[34:35], v14, v11
	v_writelane_b32 v248, s16, 3
	v_or_b32_e32 v13, v12, v10
	v_cndmask_b32_e64 v10, 0, 1, s[30:31]
	v_cndmask_b32_e64 v15, 0, 1, s[34:35]
	v_writelane_b32 v248, s17, 4
	v_cmp_gt_u32_e64 s[16:17], v11, v13
	v_cndmask_b32_e64 v10, v15, v10, s[50:51]
	v_or_b32_e32 v15, 3, v12
	v_writelane_b32 v248, s16, 5
	v_and_b32_e32 v10, 1, v10
	v_cmp_lt_u32_e64 s[34:35], v15, v11
	v_cmp_le_u32_e64 s[36:37], v15, v11
	v_writelane_b32 v248, s17, 6
	v_cmp_eq_u32_e64 s[16:17], 1, v10
	v_cndmask_b32_e64 v10, 0, 1, s[34:35]
	v_cndmask_b32_e64 v16, 0, 1, s[36:37]
	v_cndmask_b32_e64 v10, v16, v10, s[50:51]
	v_writelane_b32 v248, s16, 7
	v_and_b32_e32 v10, 1, v10
	s_cmp_lg_u32 s13, 3
	v_writelane_b32 v248, s17, 8
	v_cmp_eq_u32_e64 s[16:17], 1, v10
	v_lshlrev_b32_e32 v10, 8, v11
	v_or_b32_e32 v11, 32, v132
	v_cmp_lt_u32_e64 s[36:37], v12, v11
	v_cmp_le_u32_e64 s[38:39], v12, v11
	v_writelane_b32 v248, s16, 9
	v_cndmask_b32_e64 v16, 0, 1, s[36:37]
	v_cndmask_b32_e64 v17, 0, 1, s[38:39]
	v_writelane_b32 v248, s17, 10
	s_cselect_b64 s[16:17], -1, 0
	v_cndmask_b32_e64 v16, v17, v16, s[50:51]
	v_writelane_b32 v248, s16, 11
	v_and_b32_e32 v16, 1, v16
	v_cmp_lt_u32_e64 s[40:41], v14, v11
	v_writelane_b32 v248, s17, 12
	v_cmp_eq_u32_e64 s[16:17], 1, v16
	v_cmp_le_u32_e64 s[42:43], v14, v11
	v_cndmask_b32_e64 v16, 0, 1, s[40:41]
	v_writelane_b32 v248, s16, 13
	v_cndmask_b32_e64 v17, 0, 1, s[42:43]
	v_cndmask_b32_e64 v16, v17, v16, s[50:51]
	v_writelane_b32 v248, s17, 14
	v_cmp_gt_u32_e64 s[16:17], v11, v13
	v_and_b32_e32 v16, 1, v16
	v_cmp_lt_u32_e64 s[42:43], v15, v11
	v_writelane_b32 v248, s16, 15
	v_cmp_le_u32_e64 s[44:45], v15, v11
	v_cmp_lt_u32_e64 s[48:49], v14, v88
	v_writelane_b32 v248, s17, 16
	v_cmp_eq_u32_e64 s[16:17], 1, v16
	v_cndmask_b32_e64 v16, 0, 1, s[42:43]
	v_cndmask_b32_e64 v17, 0, 1, s[44:45]
	v_cndmask_b32_e64 v16, v17, v16, s[50:51]
	v_writelane_b32 v248, s16, 17
	v_and_b32_e32 v16, 1, v16
	v_cmp_lt_u32_e64 s[44:45], v12, v88
	v_writelane_b32 v248, s17, 18
	v_cmp_eq_u32_e64 s[16:17], 1, v16
	v_cndmask_b32_e64 v12, 0, 1, s[44:45]
	v_cndmask_b32_e64 v16, 0, 1, s[46:47]
	v_cndmask_b32_e64 v12, v16, v12, s[50:51]
	v_and_b32_e32 v12, 1, v12
	v_cmp_le_u32_e64 s[52:53], v14, v88
	v_cmp_eq_u32_e64 s[44:45], 1, v12
	v_cmp_gt_u32_e64 s[46:47], v88, v13
	v_cndmask_b32_e64 v12, 0, 1, s[48:49]
	v_cndmask_b32_e64 v13, 0, 1, s[52:53]
	v_cndmask_b32_e64 v12, v13, v12, s[50:51]
	v_writelane_b32 v248, s16, 19
	v_and_b32_e32 v12, 1, v12
	v_cmp_lt_u32_e64 s[52:53], v15, v88
	v_cmp_le_u32_e64 s[54:55], v15, v88
	s_lshr_b32 s13, s56, 7
	v_and_or_b32 v15, s12, 32, v132
	v_writelane_b32 v248, s17, 20
	v_cmp_eq_u32_e64 s[48:49], 1, v12
	v_cndmask_b32_e64 v12, 0, 1, s[52:53]
	s_lshl_b32 s16, s13, 4
	s_lshl_b32 s13, s13, 6
	v_mul_u32_u24_e32 v16, 0x110, v15
	v_subrev_co_u32_e64 v175, s[52:53], s5, v144
	v_add3_u32 v16, v171, s13, v16
	s_xor_b64 s[12:13], s[52:53], -1
	v_writelane_b32 v248, s12, 21
	s_movk_i32 s5, 0x245
	s_add_i32 s17, 0, 0x1d100
	v_writelane_b32 v248, s13, 22
	v_cmp_gt_u32_e64 s[12:13], s5, v144
	s_add_u32 s5, s96, 0x18b00000
	v_cndmask_b32_e64 v13, 0, 1, s[54:55]
	v_writelane_b32 v248, s12, 23
	v_mad_u32_u24 v177, v0, s10, 0
	v_lshlrev_b32_e32 v0, 7, v0
	v_writelane_b32 v248, s13, 24
; __device__ __forceinline__ void chunkA_item(const Args& A, LAS unsigned char* lds, int tid, int lane, int wave, int ci, int ci_next, HeadConstA& H) {
;     ...
;     {
;         const int og = wave >> 2, ms = wave & 3;
;     ...
;     {
;         const int mt = wave >> 1;
;         unsigned char* pq = (unsigned char*)A.out + CH_PQ + (size_t)ci * 24576; bf16_t* PTg = (bf16_t*)pq; float* Qg = (float*)(pq + 8192);
;         bf16_t* RHg = (bf16_t*)(A.ws + WS_RY + (size_t)ci * 16384); bf16_t* Y0g = RHg + 4096;
;         bf16x8 aX[2], aV[2], aS[2];
; #pragma unroll
;         for (int ks = 0; ks < 2; ++ks) { aX[ks] = ldsfrag(lds + CA_XT, mt * 16 + fr, ks * 32 + q4 * 8); aV[ks] = ldsfrag(lds + CA_VT, mt * 16 + fr, ks * 32 + q4 * 8);
;             aS[ks] = ldsfrag(lds + CA_XT, 64 + mt * 16 + fr, ks * 32 + q4 * 8); }
; #pragma unroll
;         for (int nn = 0; nn < 2; ++nn) { const int nt = (wave & 1) * 2 + nn, rn = nt * 16 + fr, r0 = mt * 16 + q4 * 4;
;             bf16x8 bN[2], bK[2], bMb[2], bMk[2];
; #pragma unroll
;             for (int ks = 0; ks < 2; ++ks) { bN[ks] = ldsfrag(lds + CA_NBHT, rn, ks * 32 + q4 * 8); bK[ks] = ldsfrag(lds + CA_KHT, rn, ks * 32 + q4 * 8);
;                 bMb[ks] = ldsfrag(lds + CA_NMRB, rn, ks * 32 + q4 * 8); bMk[ks] = ldsfrag(lds + CA_MRK, rn, ks * 32 + q4 * 8); }
;             f32x4 aP = {0.f, 0.f, 0.f, 0.f}, aQ = {0.f, 0.f, 0.f, 0.f}, aR = {0.f, 0.f, 0.f, 0.f}, aY = {0.f, 0.f, 0.f, 0.f};
; #pragma unroll
;             for (int ks = 0; ks < 2; ++ks) { aP = MFMA16(aX[ks], bN[ks], aP); aQ = MFMA16(aV[ks], bK[ks], aQ); aQ = MFMA16(aS[ks], bN[ks], aQ);
;                 aR = MFMA16(aX[ks], bMb[ks], aR); aY = MFMA16(aV[ks], bMk[ks], aY); aY = MFMA16(aS[ks], bMb[ks], aY); }
;             const float gj = ((LAS float*)(lds + CA_G))[rn];
;             *(u32x2*)(PTg + rn * 64 + r0) = pack4(aP[0] + (r0 + 0 == rn ? gj : 0.f), aP[1] + (r0 + 1 == rn ? gj : 0.f), aP[2] + (r0 + 2 == rn ? gj : 0.f), aP[3] + (r0 + 3 == rn ? gj : 0.f));
; #pragma unroll
;             for (int jj = 0; jj < 4; ++jj) Qg[(r0 + jj) * 64 + rn] = aQ[jj];
;             { const u32x2 rt = *(const LAS u32x2*)(lds + CA_RT + rn * 144 + r0 * 2);
;               *(u32x2*)(RHg + rn * 64 + r0) = pack4(bflo(rt.x) + aR[0], bfhi(rt.x) + aR[1], bflo(rt.y) + aR[2], bfhi(rt.y) + aR[3]); }
;             *(u32x2*)(Y0g + rn * 64 + r0) = pack4(aY[0], aY[1], aY[2], aY[3]);
;         }
	v_writelane_b32 v248, s5, 25
	s_addc_u32 s43, s97, 0
	s_add_i32 s5, s16, 64
	v_cndmask_b32_e64 v12, v13, v12, s[50:51]
	v_sub_u32_e32 v19, 0, v0
	v_or_b32_e32 v0, s5, v132
	v_and_b32_e32 v12, 1, v12
	v_mul_lo_u32 v0, v0, s4
	v_cmp_eq_u32_e64 s[50:51], 1, v12
	v_or_b32_e32 v12, s16, v132
	v_add_u32_e32 v20, 0, v0
	v_or_b32_e32 v0, s16, v2
	v_mul_lo_u32 v12, v12, s4
	v_add_u32_e32 v173, 0xfc00, v16
	v_mov_b32_e32 v18, 0x900
	v_add_u32_e32 v174, 0x10d00, v16
	v_and_b32_e32 v16, 3, v144
	v_mov_b32_e32 v2, s7
	s_add_i32 s12, 0, 0x21900
	v_lshlrev_b32_e32 v27, 6, v0
	v_add_u32_e32 v14, s17, v12
	v_or_b32_e32 v17, 16, v15
	v_mad_u32_u24 v18, v15, s4, v18
	v_lshl_add_u32 v176, v16, 6, s11
	v_cmp_eq_u32_e64 s[54:55], 0, v16
	v_cmp_eq_u32_e64 s[56:57], 1, v16
	v_cmp_eq_u32_e64 s[58:59], 2, v16
	v_cmp_eq_u32_e64 s[64:65], 3, v16
	v_add_u32_e32 v16, 0, v12
	v_or_b32_e32 v12, 1, v0
	v_or_b32_e32 v21, 3, v0
	v_or_b32_e32 v22, 2, v0
	v_mad_u32_u24 v25, v15, s4, v2
	v_mov_b32_e32 v2, s12
	v_or_b32_e32 v28, 64, v27
	v_or_b32_e32 v29, 0x80, v27
	v_or_b32_e32 v30, 0xc0, v27
	v_cmp_gt_u32_e32 vcc, 8, v144
	v_mad_u32_u24 v1, v147, s4, 0
	v_lshlrev_b32_e32 v3, 4, v207
	v_lshlrev_b32_e32 v4, 5, v144
	v_mad_u32_u24 v8, v145, s4, 0
	v_mul_u32_u24_e32 v6, 0x110, v145
	v_lshlrev_b32_e32 v9, 8, v132
	v_lshlrev_b32_e32 v11, 8, v11
	v_lshlrev_b32_e32 v13, 8, v88
	v_mul_u32_u24_e32 v172, 0x90, v15
	v_lshl_add_u32 v23, v0, 1, 0
	v_mad_u32_u24 v24, v15, s4, 0
	v_mad_u32_u24 v26, v15, s4, v2
	v_lshl_add_u32 v179, v15, 2, s6
	v_cmp_eq_u32_e64 s[20:21], v0, v15
	v_cmp_eq_u32_e64 s[10:11], v12, v15
	v_cmp_eq_u32_e64 s[52:53], v21, v15
	v_cmp_eq_u32_e64 s[4:5], v22, v15
	v_lshlrev_b32_e32 v2, 6, v15
	v_add_u32_e32 v15, 0, v18
	v_add_u32_e32 v31, s7, v18
	v_add_u32_e32 v18, s12, v18
	v_cmp_eq_u32_e64 s[12:13], v12, v17
	v_lshlrev_b32_e32 v12, 6, v17
	v_lshlrev_b32_e32 v78, 3, v207
	v_lshl_add_u64 v[82:83], s[60:61], 0, v[72:73]
	v_lshl_add_u32 v164, v145, 1, 0
	v_add_u32_e32 v165, s6, v137
	v_mul_u32_u24_e32 v169, 0x90, v132
	v_mul_u32_u24_e32 v170, 0x90, v88
	v_add_u32_e32 v178, 0xfc00, v177
	v_mov_b32_e32 v85, v73
	v_mov_b32_e32 v87, v73
	v_mov_b32_e32 v91, v73
	v_mov_b32_e32 v93, v73
	v_lshl_add_u32 v180, v17, 2, s6
	v_cmp_eq_u32_e64 s[6:7], v0, v17
	v_cmp_eq_u32_e64 s[16:17], v21, v17
	v_cmp_eq_u32_e64 s[18:19], v22, v17
	v_mov_b32_e32 v95, v73
	v_mov_b32_e32 v97, v73
	v_mov_b32_e32 v99, v73
	v_mov_b32_e32 v101, v73
	s_mov_b32 s29, -1
	s_xor_b64 s[26:27], vcc, -1
	s_movk_i32 s22, 0x1c00
	v_add_u32_e32 v181, s79, v8
	v_add_u32_e32 v182, s78, v6
	v_bfe_u32 v183, v144, 4, 4
	v_lshlrev_b32_e32 v183, 10, v183
	v_and_b32_e32 v184, 3, v144
	v_lshl_add_u32 v183, v184, 6, v183
	v_bfe_u32 v184, v144, 2, 2
	v_lshl_add_u32 v183, v184, 2, v183
	v_add_u32_e32 v183, 0x19100, v183
	v_add_u32_e32 v187, v14, v89
	v_add_u32_e32 v188, v16, v89
	v_add_u32_e32 v189, v20, v89
	v_add_u32_e32 v190, v24, v89
	v_add_u32_e32 v191, v25, v89
	v_add_u32_e32 v192, v26, v89
	v_add_u32_e32 v193, v23, v172
	v_add_u32_e32 v194, v15, v89
	v_add_u32_e32 v195, v31, v89
	v_add_u32_e32 v196, v18, v89
	v_add_u32_e32 v197, 0, v4
	v_add_u32_e32 v198, v1, v3
	v_add_u32_e32 v199, v5, v89
	v_mov_b32_e32 v224, v73
	v_mov_b32_e32 v225, v73
	v_mov_b32_e32 v200, 0x640
	v_mov_b32_e32 v201, 0x600
	v_add_u32_e32 v202, v177, v19
	v_lshrrev_b32_e32 v32, 8, v144
	v_lshlrev_b32_e32 v102, 10, v32
	v_bfe_u32 v32, v144, 7, 1
	v_lshl_add_u32 v102, v32, 9, v102
	v_bfe_u32 v32, v144, 5, 1
	v_lshl_add_u32 v102, v32, 8, v102
	v_and_b32_e32 v32, 15, v144
	v_lshl_add_u32 v102, v32, 4, v102
	v_bfe_u32 v32, v144, 4, 1
	v_lshl_add_u32 v102, v32, 3, v102
	v_bfe_u32 v32, v144, 6, 1
	v_lshlrev_b32_e32 v104, 12, v32
	v_add_u32_e32 v106, 0x800, v104
	v_lshrrev_b32_e32 v33, 7, v144
	v_lshlrev_b32_e32 v84, 10, v33
	v_lshl_add_u32 v84, v32, 9, v84
	v_and_b32_e32 v33, 63, v144
	v_lshl_add_u32 v84, v33, 2, v84
	v_add_u32_e32 v86, 64, v84
	v_add_u32_e32 v90, 0x80, v84
	v_add_u32_e32 v92, 0xc0, v84
	v_add_u32_e32 v94, 0x100, v84
	v_add_u32_e32 v96, 0x140, v84
	v_add_u32_e32 v98, 0x180, v84
	v_add_u32_e32 v100, 0x1c0, v84
	s_mov_b32 s28, s2
	s_branch .LBB0_147

; #define LAS __attribute__((address_space(3)))
; __device__ __forceinline__ void chunkA_item(const Args& A, LAS unsigned char* lds, int tid, int lane, int wave, int ci, int ci_next, HeadConstA& H) {
;     ...
;     {
;         const int mt = wave >> 1;
;         unsigned char* pq = (unsigned char*)A.out + CH_PQ + (size_t)ci * 24576; bf16_t* PTg = (bf16_t*)pq; float* Qg = (float*)(pq + 8192);
;         bf16_t* RHg = (bf16_t*)(A.ws + WS_RY + (size_t)ci * 16384); bf16_t* Y0g = RHg + 4096;
;         bf16x8 aX[2], aV[2], aS[2];
; #pragma unroll
;         for (int ks = 0; ks < 2; ++ks) { aX[ks] = ldsfrag(lds + CA_XT, mt * 16 + fr, ks * 32 + q4 * 8); aV[ks] = ldsfrag(lds + CA_VT, mt * 16 + fr, ks * 32 + q4 * 8);
;             aS[ks] = ldsfrag(lds + CA_XT, 64 + mt * 16 + fr, ks * 32 + q4 * 8); }
; #pragma unroll
;         for (int nn = 0; nn < 2; ++nn) { const int nt = (wave & 1) * 2 + nn, rn = nt * 16 + fr, r0 = mt * 16 + q4 * 4;
;             bf16x8 bN[2], bK[2], bMb[2], bMk[2];
; #pragma unroll
;             for (int ks = 0; ks < 2; ++ks) { bN[ks] = ldsfrag(lds + CA_NBHT, rn, ks * 32 + q4 * 8); bK[ks] = ldsfrag(lds + CA_KHT, rn, ks * 32 + q4 * 8);
;                 bMb[ks] = ldsfrag(lds + CA_NMRB, rn, ks * 32 + q4 * 8); bMk[ks] = ldsfrag(lds + CA_MRK, rn, ks * 32 + q4 * 8); }
;             f32x4 aP = {0.f, 0.f, 0.f, 0.f}, aQ = {0.f, 0.f, 0.f, 0.f}, aR = {0.f, 0.f, 0.f, 0.f}, aY = {0.f, 0.f, 0.f, 0.f};
; #pragma unroll
;             for (int ks = 0; ks < 2; ++ks) { aP = MFMA16(aX[ks], bN[ks], aP); aQ = MFMA16(aV[ks], bK[ks], aQ); aQ = MFMA16(aS[ks], bN[ks], aQ);
;                 aR = MFMA16(aX[ks], bMb[ks], aR); aY = MFMA16(aV[ks], bMk[ks], aY); aY = MFMA16(aS[ks], bMb[ks], aY); }
;             const float gj = ((LAS float*)(lds + CA_G))[rn];
;             *(u32x2*)(PTg + rn * 64 + r0) = pack4(aP[0] + (r0 + 0 == rn ? gj : 0.f), aP[1] + (r0 + 1 == rn ? gj : 0.f), aP[2] + (r0 + 2 == rn ? gj : 0.f), aP[3] + (r0 + 3 == rn ? gj : 0.f));
; #pragma unroll
;             for (int jj = 0; jj < 4; ++jj) Qg[(r0 + jj) * 64 + rn] = aQ[jj];
;             { const u32x2 rt = *(const LAS u32x2*)(lds + CA_RT + rn * 144 + r0 * 2);
;               *(u32x2*)(RHg + rn * 64 + r0) = pack4(bflo(rt.x) + aR[0], bfhi(rt.x) + aR[1], bflo(rt.y) + aR[2], bfhi(rt.y) + aR[3]); }
;             *(u32x2*)(Y0g + rn * 64 + r0) = pack4(aY[0], aY[1], aY[2], aY[3]);
;         }
.LBB0_146:
	s_or_b64 exec, exec, s[78:79]
	s_waitcnt lgkmcnt(0)
	s_barrier
	ds_read_b128 v[40:43], v188
	ds_read_b128 v[32:35], v190 offset:36864
	ds_read_b128 v[36:39], v188 offset:55296
	ds_read_b128 v[48:51], v189
	ds_read_b128 v[44:47], v190 offset:46080
	ds_read_b128 v[52:55], v192
	s_waitcnt lgkmcnt(4)
	v_mfma_f32_16x16x32_bf16 v[56:59], v[40:43], v[32:35], 0
	s_mul_i32 s24, s28, 0x6000
	s_mul_hi_i32 s25, s28, 0x6000
	s_add_u32 s24, s86, s24
	s_waitcnt lgkmcnt(1)
	v_mfma_f32_16x16x32_bf16 v[44:47], v[36:39], v[44:47], 0
	s_addc_u32 s25, s87, s25
	ds_read_b128 v[64:67], v191
	s_lshl_b64 s[28:29], s[28:29], 14
	v_mfma_f32_16x16x32_bf16 v[60:63], v[48:51], v[32:35], v[44:47]
	v_readlane_b32 s30, v248, 25
	s_add_u32 s30, s30, s28
	s_addc_u32 s31, s43, s29
	s_nop 0
	ds_read_b128 v[44:47], v188 offset:64
	s_waitcnt lgkmcnt(2)
	v_mfma_f32_16x16x32_bf16 v[32:35], v[36:39], v[52:55], 0
	ds_read_b128 v[52:55], v188 offset:55360
	ds_read_b128 v[68:71], v190 offset:36928
	v_mov_b32_e32 v103, v73
	s_add_u32 s28, s24, 0x2000
	s_waitcnt lgkmcnt(3)
	v_mfma_f32_16x16x32_bf16 v[214:217], v[48:51], v[64:67], v[32:35]
	s_nop 2
	ds_read_b128 v[32:35], v189 offset:64
	ds_read_b128 v[108:111], v190 offset:46144
	ds_read_b128 v[218:221], v192 offset:64
	ds_read_b32 v72, v179
	s_waitcnt lgkmcnt(2)
	v_mfma_f32_16x16x32_bf16 v[60:63], v[52:55], v[108:111], v[60:63]
	v_lshl_add_u64 v[112:113], s[24:25], 0, v[102:103]
	v_mov_b32_e32 v105, v73
	s_addc_u32 s29, s25, 0
	v_mfma_f32_16x16x32_bf16 v[56:59], v[44:47], v[68:71], v[56:59]
	ds_read_b64 v[222:223], v193 offset:27648
	v_lshl_add_u64 v[110:111], s[30:31], 0, v[102:103]
	s_mov_b64 s[24:25], 0x2000
	v_mfma_f32_16x16x32_bf16 v[60:63], v[32:35], v[68:71], v[60:63]
	ds_read_b128 v[68:71], v191 offset:64
	v_lshl_add_u64 v[108:109], v[110:111], 0, s[24:25]
	v_mov_b32_e32 v107, v73
	s_waitcnt lgkmcnt(3)
	v_mfma_f32_16x16x32_bf16 v[214:217], v[52:55], v[218:221], v[214:217]
	s_waitcnt lgkmcnt(2)
	v_cndmask_b32_e64 v219, 0, v72, s[10:11]
	v_cndmask_b32_e64 v218, 0, v72, s[20:21]
	v_pk_add_f32 v[56:57], v[56:57], v[218:219]
	v_cndmask_b32_e64 v219, 0, v72, s[52:53]
	v_cndmask_b32_e64 v218, 0, v72, s[4:5]
	v_pk_add_f32 v[58:59], v[58:59], v[218:219]
	v_cvt_pk_bf16_f32 v218, v56, v57
	v_cvt_pk_bf16_f32 v219, v58, v59
	v_mfma_f32_16x16x32_bf16 v[56:59], v[40:43], v[64:67], 0
	v_lshl_add_u64 v[64:65], v[112:113], 0, v[104:105]
	global_store_dwordx2 v[64:65], v[218:219], off
	v_lshl_add_u64 v[64:65], v[84:85], 2, s[28:29]
	global_store_dwordx4 v[64:65], v[60:63], off
	v_lshl_add_u64 v[64:65], v[86:87], 2, s[28:29]
	ds_read_b128 v[64:67], v194 offset:46080
	v_lshl_add_u64 v[60:61], v[90:91], 2, s[28:29]
	s_waitcnt lgkmcnt(1)
	v_mfma_f32_16x16x32_bf16 v[218:221], v[44:47], v[68:71], v[56:59]
	v_lshl_add_u64 v[60:61], v[92:93], 2, s[28:29]
	ds_read_b128 v[56:59], v194 offset:36864
	ds_read_b128 v[60:63], v196
	s_waitcnt lgkmcnt(2)
	v_mfma_f32_16x16x32_bf16 v[64:67], v[36:39], v[64:67], 0
	ds_read_b32 v72, v180
	v_lshlrev_b32_e32 v230, 16, v222
	v_and_b32_e32 v231, 0xffff0000, v222
	v_mfma_f32_16x16x32_bf16 v[68:71], v[32:35], v[68:71], v[214:217]
	v_add_f32_e64 v218, v218, v230
	v_add_f32_e64 v219, v219, v231
	ds_read_b128 v[230:233], v194 offset:36928
	s_cmpk_gt_i32 s42, 0xfff
	s_waitcnt lgkmcnt(3)
	v_mfma_f32_16x16x32_bf16 v[214:217], v[40:43], v[56:59], 0
	v_mfma_f32_16x16x32_bf16 v[226:229], v[48:51], v[56:59], v[64:67]
	ds_read_b128 v[56:59], v195
	s_waitcnt lgkmcnt(3)
	v_mfma_f32_16x16x32_bf16 v[36:39], v[36:39], v[60:63], 0
	v_lshlrev_b32_e32 v60, 16, v223
	v_and_b32_e32 v61, 0xffff0000, v223
	s_waitcnt lgkmcnt(0)
	v_mfma_f32_16x16x32_bf16 v[64:67], v[48:51], v[56:59], v[36:39]
	v_add_f32_e64 v48, v220, v60
	v_add_f32_e64 v49, v221, v61
	v_cvt_pk_bf16_f32 v50, v218, v219
	v_cvt_pk_bf16_f32 v51, v48, v49
	v_lshl_add_u64 v[48:49], v[110:111], 0, v[104:105]
	global_store_dwordx2 v[48:49], v[50:51], off
	v_cvt_pk_bf16_f32 v48, v68, v69
	v_cvt_pk_bf16_f32 v49, v70, v71
	v_lshl_add_u64 v[50:51], v[108:109], 0, v[104:105]
	ds_read_b128 v[36:39], v194 offset:46144
	ds_read_b128 v[68:71], v196 offset:64
	global_store_dwordx2 v[50:51], v[48:49], off
	ds_read_b128 v[48:51], v195 offset:64
	v_mfma_f32_16x16x32_bf16 v[40:43], v[40:43], v[56:59], 0
	v_lshl_add_u64 v[56:57], v[96:97], 2, s[28:29]
	v_mfma_f32_16x16x32_bf16 v[60:63], v[44:47], v[230:233], v[214:217]
	s_waitcnt lgkmcnt(0)
	v_mfma_f32_16x16x32_bf16 v[40:43], v[44:47], v[48:51], v[40:43]
	ds_read_b64 v[44:45], v193 offset:29952
	v_mfma_f32_16x16x32_bf16 v[36:39], v[52:55], v[36:39], v[226:229]
	v_mfma_f32_16x16x32_bf16 v[52:55], v[52:55], v[68:71], v[64:67]
	v_mov_b32_e32 v68, v209
	v_mov_b32_e32 v69, v208
	v_mov_b32_e32 v70, v203
	v_cndmask_b32_e64 v64, 0, v72, s[6:7]
	v_add_f32_e32 v64, v60, v64
	v_cndmask_b32_e64 v60, 0, v72, s[12:13]
	v_mfma_f32_16x16x32_bf16 v[36:39], v[32:35], v[230:233], v[36:39]
	v_add_f32_e32 v65, v61, v60
	v_cndmask_b32_e64 v61, 0, v72, s[16:17]
	v_cndmask_b32_e64 v60, 0, v72, s[18:19]
	v_pk_add_f32 v[60:61], v[62:63], v[60:61]
	v_cvt_pk_bf16_f32 v62, v64, v65
	v_cvt_pk_bf16_f32 v63, v60, v61
	v_lshl_add_u64 v[60:61], v[112:113], 0, v[106:107]
	global_store_dwordx2 v[60:61], v[62:63], off
	v_lshl_add_u64 v[60:61], v[94:95], 2, s[28:29]
	global_store_dwordx4 v[60:61], v[36:39], off
	v_mfma_f32_16x16x32_bf16 v[32:35], v[32:35], v[48:51], v[52:55]
	s_waitcnt lgkmcnt(0)
	v_lshlrev_b32_e32 v36, 16, v44
	v_and_b32_e32 v37, 0xffff0000, v44
	v_lshlrev_b32_e32 v38, 16, v45
	v_and_b32_e32 v39, 0xffff0000, v45
	v_pk_add_f32 v[36:37], v[40:41], v[36:37]
	v_pk_add_f32 v[38:39], v[42:43], v[38:39]
	v_cvt_pk_bf16_f32 v36, v36, v37
	v_cvt_pk_bf16_f32 v37, v38, v39
	v_lshl_add_u64 v[38:39], v[110:111], 0, v[106:107]
	v_cvt_pk_bf16_f32 v32, v32, v33
	v_cvt_pk_bf16_f32 v33, v34, v35
	v_lshl_add_u64 v[34:35], v[108:109], 0, v[106:107]
	global_store_dwordx2 v[38:39], v[36:37], off
	global_store_dwordx2 v[34:35], v[32:33], off
	s_waitcnt lgkmcnt(0)
	s_barrier
	v_mov_b64_e32 v[34:35], v[30:31]
	v_mov_b64_e32 v[38:39], v[26:27]
	v_mov_b64_e32 v[42:43], v[14:15]
	v_mov_b64_e32 v[46:47], v[10:11]
	v_mov_b64_e32 v[50:51], v[22:23]
	v_mov_b64_e32 v[54:55], v[18:19]
	v_mov_b64_e32 v[58:59], v[6:7]
	v_mov_b64_e32 v[62:63], v[2:3]
	s_mov_b32 s28, s42
	v_mov_b32_e32 v64, v213
	v_mov_b32_e32 v65, v212
	v_mov_b32_e32 v66, v211
	v_mov_b32_e32 v67, v210
	v_mov_b64_e32 v[32:33], v[28:29]
	v_mov_b64_e32 v[36:37], v[24:25]
	v_mov_b64_e32 v[40:41], v[12:13]
	v_mov_b64_e32 v[44:45], v[8:9]
	v_mov_b64_e32 v[48:49], v[20:21]
	v_mov_b64_e32 v[52:53], v[16:17]
	v_mov_b64_e32 v[56:57], v[4:5]
	v_mov_b64_e32 v[60:61], v[0:1]
	s_mov_b32 s29, s23
	s_cbranch_scc1 .LBB0_261

; #define LAS __attribute__((address_space(3)))
; __device__ __forceinline__ void chunkB_item(const Args& A, LAS unsigned char* lds, int tid, int lane, int wave, int bh) {
;     const int fr = lane & 15, q4 = lane >> 4, mt = wave >> 1, nt0 = (wave & 1) * 2, v0 = mt * 16 + q4 * 4;
;     const int h = bh & 7, b = bh >> 3, colg = h * 64 + v0;
;     const bf16_t* Z = (const bf16_t*)(A.ws + WS_Z); bf16_t* MIX = (bf16_t*)(A.ws + WS_XN);
;     LAS float* ST = (LAS float*)(lds + 18432);
;     f32x4 acc[2] = {{0.f, 0.f, 0.f, 0.f}, {0.f, 0.f, 0.f, 0.f}};
;     ...
;     B_LOAD(p0, q0, 0); B_LOADY(r0_, ya0, zc0, zp0, zg0, bc0, 0);
.LBB0_275:
	s_or_b64 exec, exec, s[12:13]
	v_mov_b32_e32 v0, s34
	s_waitcnt lgkmcnt(0)
	s_barrier
	ds_read_b32 v0, v0
	s_movk_i32 s13, 0x7f
	s_mov_b64 s[14:15], -1
	s_waitcnt lgkmcnt(0)
	s_barrier
	v_cmp_lt_i32_e32 vcc, s13, v0
	v_readfirstlane_b32 s12, v0
	s_cbranch_vccnz .LBB0_270
	s_lshr_b32 s98, s12, 3
	s_mul_i32 s98, s98, 0xe00000
	s_add_u32 s98, s94, s98
	s_addc_u32 s99, s95, 0
	s_sub_u32 s98, s98, 0x1c00
	s_subb_u32 s99, s99, 0
	v_lshrrev_b32_e32 v240, 4, v144
	v_lshrrev_b32_e32 v241, 6, v144
	v_lshl_add_u32 v240, v241, 2, v240
	v_and_b32_e32 v241, 15, v144
	v_mul_u32_u24_e32 v242, 0x90, v240
	v_lshl_add_u32 v242, v241, 3, v242
	v_add_u32_e32 v242, 0x6000, v242
	v_mul_u32_u24_e32 v240, 0x1c00, v240
	v_lshl_add_u32 v240, v241, 3, v240
	s_and_b32 s22, s12, 7
	s_lshl_b32 s22, s22, 7
	s_add_i32 s22, s22, 0x800
	v_add_u32_e32 v240, s22, v240
	v_add_u32_e32 v240, 0x1c00, v240
	v_add_u32_e32 v241, 0x7000, v240
	v_mul_u32_u24_e32 v243, 0x90, v96
	v_lshl_add_u32 v243, v92, 1, v243
	v_add_u32_e32 v243, 0x6000, v243
	global_load_dwordx2 v[182:183], v240, s[98:99]
	global_load_dwordx2 v[188:189], v241, s[98:99]
	global_load_dwordx2 v[184:185], v240, s[98:99] offset:1280
	global_load_dwordx2 v[190:191], v241, s[98:99] offset:1280
	s_and_b32 s38, s12, 7
	v_mov_b32_e32 v244, s38
	v_lshl_add_u32 v244, v244, 6, v92
	v_lshlrev_b32_e32 v244, 2, v244
	v_readlane_b32 s20, v249, 10
	v_readlane_b32 s21, v249, 11
	v_readlane_b32 s22, v249, 12
	v_readlane_b32 s23, v249, 13
	s_nop 4
	global_load_dwordx4 v[228:231], v244, s[20:21]
	global_load_dwordx4 v[250:253], v244, s[22:23]
	global_load_dwordx2 v[232:233], v244, s[6:7]
	global_load_dwordx2 v[254:255], v244, s[6:7] offset:8
	s_ashr_i32 s13, s12, 31
	s_mul_i32 s14, s12, 0xc0000
	s_mul_hi_i32 s15, s12, 0xc0000
	s_add_u32 s14, s86, s14
	s_addc_u32 s15, s87, s15
	s_add_u32 s16, s14, 0x2000
	v_lshlrev_b32_e32 v94, 8, v91
	v_lshl_add_u32 v94, v132, 4, v94
	v_add_u32_e32 v234, v94, v124
	v_add_u32_e32 v235, v94, v126
	v_lshrrev_b32_e32 v236, 7, v144
	v_lshlrev_b32_e32 v236, 12, v236
	v_bfe_u32 v237, v144, 6, 1
	v_lshl_add_u32 v236, v237, 11, v236
	v_and_b32_e32 v237, 63, v144
	v_lshl_add_u32 v236, v237, 4, v236
	v_add_u32_e32 v236, 0x2000, v236
	v_add_u32_e32 v237, 0x400, v236
	v_add_u32_e32 v238, v148, v124
	v_add_u32_e32 v238, 0x2000, v238
	v_add_u32_e32 v239, v148, v126
	v_add_u32_e32 v239, 0x2000, v239
	v_mul_u32_u24_e32 v245, 0x1c00, v96
	v_lshl_add_u32 v245, v92, 1, v245
	v_mov_b32_e32 v246, s38
	v_lshl_add_u32 v245, v246, 7, v245
	v_add_u32_e32 v245, 0x800, v245
	global_load_dwordx4 v[210:213], v236, s[14:15]
	global_load_dwordx4 v[40:43], v237, s[14:15]
	s_addc_u32 s17, s15, 0
	v_lshl_add_u64 v[8:9], s[14:15], 0, v[94:95]
	v_mov_b32_e32 v125, v95
	v_mov_b32_e32 v127, v95
	v_lshl_add_u64 v[4:5], v[8:9], 0, v[124:125]
	v_lshl_add_u64 v[10:11], v[98:99], 2, s[16:17]
	v_lshl_add_u64 v[12:13], v[100:101], 2, s[16:17]
	v_lshl_add_u64 v[14:15], v[102:103], 2, s[16:17]
	v_lshl_add_u64 v[8:9], v[8:9], 0, v[126:127]
	global_load_dwordx4 v[0:3], v[4:5], off
	s_nop 0
	global_load_dwordx4 v[4:7], v[4:5], off offset:1024
	v_lshl_add_u64 v[16:17], v[104:105], 2, s[16:17]
	global_load_dwordx4 v[36:39], v[8:9], off
	global_load_dwordx4 v[20:23], v[8:9], off offset:1024
	v_lshl_add_u64 v[8:9], v[108:109], 2, s[16:17]
	v_lshl_add_u64 v[10:11], v[110:111], 2, s[16:17]
	v_lshl_add_u64 v[12:13], v[112:113], 2, s[16:17]
	v_lshl_add_u64 v[14:15], v[114:115], 2, s[16:17]
	s_ashr_i32 s14, s12, 3
	s_lshl_b64 s[16:17], s[12:13], 19
	s_add_u32 s18, s3, s16
	s_addc_u32 s19, s11, s17
	v_mov_b32_e32 v149, v95
	v_lshl_add_u64 v[8:9], s[18:19], 0, v[148:149]
	s_ashr_i32 s15, s14, 31
	v_lshl_add_u64 v[16:17], s[18:19], 0, v[94:95]
	v_lshl_add_u64 v[18:19], v[8:9], 0, s[8:9]
	s_lshl_b64 s[16:17], s[14:15], 11
	v_lshl_add_u64 v[12:13], v[16:17], 0, v[124:125]
	v_lshl_add_u64 v[24:25], v[18:19], 0, v[124:125]
	global_load_dwordx4 v[8:11], v[12:13], off
	s_nop 0
	global_load_dwordx4 v[12:15], v[12:13], off offset:1024
	v_or_b32_e32 v27, s16, v96
	global_load_dwordx2 v[196:197], v[24:25], off
	v_mov_b64_e32 v[24:25], s[94:95]
	v_lshl_add_u32 v26, s38, 6, v92
	v_mad_u64_u32 v[24:25], s[18:19], v27, s35, v[24:25]
	v_mad_i32_i24 v25, s17, v147, v25
	v_lshlrev_b32_e32 v150, 1, v26
	v_mov_b32_e32 v151, v95
	v_lshl_add_u64 v[24:25], v[24:25], 0, v[150:151]
	global_load_dwordx2 v[174:175], v[24:25], off offset:2048
	v_mov_b32_e32 v170, v95
	v_mov_b32_e32 v171, v95
	s_and_saveexec_b64 s[18:19], s[4:5]
	s_cbranch_execz .LBB0_278
	v_add_co_u32_e32 v28, vcc, 0xfffff000, v24
	s_nop 1
	v_addc_co_u32_e32 v29, vcc, -1, v25, vcc
	global_load_dwordx2 v[170:171], v[28:29], off offset:-1024

; __device__ __forceinline__ void chunkB_item(const Args& A, LAS unsigned char* lds, int tid, int lane, int wave, int bh) {
;     ...
;     bf16x8 p0[2][2], p1[2][2]; f32x4 q0[2], q1[2];
;     bf16x8 r0_[2][2], r1_[2][2]; u32x2 ya0[2], ya1[2], zc0[2], zc1[2], zp0[2], zp1[2], zg0[2], zg1[2]; float bc0[2], bc1[2];
;     B_LOAD(p0, q0, 0); B_LOADY(r0_, ya0, zc0, zp0, zg0, bc0, 0);
; #pragma unroll 1
;     for (int c = 0; c < 32; ++c) {
;         const int cn = c + 1 < 32 ? c + 1 : 31;
;         B_LOAD(p1, q1, cn); B_LOADY(r1_, ya1, zc1, zp1, zg1, bc1, cn);
;         B_STEP(p0, q0, r0_, ya0, zc0, zp0, zg0, bc0, c);
; #pragma unroll
;         for (int nn = 0; nn < 2; ++nn) { p0[nn][0] = p1[nn][0]; p0[nn][1] = p1[nn][1]; q0[nn] = q1[nn]; r0_[nn][0] = r1_[nn][0]; r0_[nn][1] = r1_[nn][1];
;             ya0[nn] = ya1[nn]; zc0[nn] = zc1[nn]; zp0[nn] = zp1[nn]; zg0[nn] = zg1[nn]; bc0[nn] = bc1[nn]; }
.LBB0_279:
	s_or_b64 exec, exec, s[22:23]
	s_waitcnt lgkmcnt(0)
	s_barrier
	v_mov_b32_dpp v170, v174 row_shr:1 row_mask:0xf bank_mask:0xf
	v_mov_b32_dpp v171, v175 row_shr:1 row_mask:0xf bank_mask:0xf
	v_mov_b32_dpp v164, v174 row_ror:1 row_mask:0xf bank_mask:0xf
	v_mov_b32_dpp v165, v175 row_ror:1 row_mask:0xf bank_mask:0xf
	v_mov_b32_dpp v164, v168 row_shr:1 row_mask:0xf bank_mask:0xf
	v_mov_b32_dpp v165, v169 row_shr:1 row_mask:0xf bank_mask:0xf
	global_load_dwordx4 v[8:11], v234, s[100:101]
	ds_read2st64_b64 v[20:23], v141 offset0:36 offset1:37
	s_waitcnt lgkmcnt(1)
	ds_read2st64_b64 v[36:39], v141 offset0:38 offset1:39
	v_lshlrev_b32_e32 v42, 16, v176
	v_and_b32_e32 v43, 0xffff0000, v176
	v_lshlrev_b32_e32 v40, 16, v174
	s_waitcnt lgkmcnt(1)
	v_pk_add_f32 v[20:21], v[20:21], 0 op_sel_hi:[1,0]
	v_and_b32_e32 v41, 0xffff0000, v174
	v_pk_add_f32 v[20:21], v[20:21], v[22:23]
	global_load_dwordx4 v[12:15], v234, s[100:101] offset:1024
	v_mul_f32_e32 v23, 0xbfb8aa3b, v42
	s_waitcnt lgkmcnt(0)
	v_pk_add_f32 v[20:21], v[20:21], v[36:37]
	v_exp_f32_e32 v23, v23
	v_pk_add_f32 v[20:21], v[20:21], v[38:39]
	v_lshlrev_b32_e32 v36, 16, v170
	v_pk_mul_f32 v[20:21], v[20:21], s[10:11] op_sel_hi:[1,0]
	v_add_f32_e32 v23, 1.0, v23
	v_fma_f32 v22, -v20, v20, v21
	v_max_f32_e32 v22, 0, v22
	v_add_f32_e32 v22, 0x3a27c5ac, v22
	global_load_dwordx4 v[44:47], v235, s[100:101]
	v_rcp_f32_e32 v38, v23
	v_mul_f32_e32 v23, 0xbfb8aa3b, v43
	v_rsq_f32_e32 v22, v22
	v_exp_f32_e32 v23, v23
	v_and_b32_e32 v37, 0xffff0000, v170
	v_pk_add_f32 v[56:57], v[198:199], v[20:21] op_sel_hi:[1,0] neg_lo:[0,1] neg_hi:[0,1]
	v_pk_add_f32 v[36:37], v[36:37], v[40:41] neg_lo:[0,1] neg_hi:[0,1]
	v_pk_mul_f32 v[56:57], v[56:57], v[22:23] op_sel_hi:[1,0]
	global_load_dwordx4 v[48:51], v235, s[100:101] offset:1024
	v_add_f32_e32 v23, 1.0, v23
	s_waitcnt vmcnt(17)
	v_pk_fma_f32 v[36:37], v[36:37], v[232:233], v[40:41]
	v_lshlrev_b32_e32 v40, 16, v177
	v_rcp_f32_e32 v39, v23
	v_mul_f32_e32 v23, 0xbfb8aa3b, v40
	v_exp_f32_e32 v23, v23
	v_pk_fma_f32 v[56:57], v[228:229], v[56:57], v[250:251]
	v_and_b32_e32 v41, 0xffff0000, v177
	v_pk_fma_f32 v[36:37], v[172:173], v[36:37], v[56:57] op_sel_hi:[0,1,1]
	v_add_f32_e32 v23, 1.0, v23
	v_rcp_f32_e32 v56, v23
	global_load_dwordx2 v[178:179], v238, s[100:101]
	v_mul_f32_e32 v23, 0xbfb8aa3b, v41
	v_exp_f32_e32 v23, v23
	v_pk_add_f32 v[20:21], v[196:197], v[20:21] op_sel_hi:[1,0] neg_lo:[0,1] neg_hi:[0,1]
	v_pk_mul_f32 v[38:39], v[38:39], v[42:43]
	v_lshlrev_b32_e32 v42, 16, v171
	v_pk_mul_f32 v[20:21], v[20:21], v[22:23] op_sel_hi:[1,0]
	v_add_f32_e32 v22, 1.0, v23
	v_rcp_f32_e32 v57, v22
	v_pk_mul_f32 v[36:37], v[38:39], v[36:37]
	global_load_dwordx2 v[180:181], v239, s[100:101]
	v_lshlrev_b32_e32 v38, 16, v175
	v_and_b32_e32 v39, 0xffff0000, v175
	v_and_b32_e32 v43, 0xffff0000, v171
	v_pk_add_f32 v[22:23], v[42:43], v[38:39] neg_lo:[0,1] neg_hi:[0,1]
	v_pk_fma_f32 v[20:21], v[230:231], v[20:21], v[252:253]
	v_pk_fma_f32 v[22:23], v[22:23], v[254:255], v[38:39]
	v_lshl_add_u64 v[42:43], v[160:161], 0, s[20:21]
	v_pk_fma_f32 v[20:21], v[172:173], v[22:23], v[20:21] op_sel_hi:[0,1,1]
	v_pk_mul_f32 v[22:23], v[56:57], v[40:41]
	v_cvt_pk_bf16_f32 v40, v36, v37
	v_pk_mul_f32 v[38:39], v[22:23], v[20:21]
	ds_read2st64_b64 v[20:23], v143 offset0:36 offset1:37
	v_cvt_pk_bf16_f32 v41, v38, v39
	ds_read2st64_b64 v[36:39], v143 offset0:38 offset1:39
	global_store_dwordx2 v[42:43], v[40:41], off
	v_lshlrev_b32_e32 v40, 16, v164
	s_waitcnt lgkmcnt(1)
	v_pk_add_f32 v[20:21], v[20:21], 0 op_sel_hi:[1,0]
	v_and_b32_e32 v41, 0xffff0000, v164
	v_pk_add_f32 v[20:21], v[20:21], v[22:23]
	s_waitcnt lgkmcnt(0)
	v_pk_add_f32 v[20:21], v[20:21], v[36:37]
	v_lshlrev_b32_e32 v36, 16, v168
	v_pk_add_f32 v[20:21], v[20:21], v[38:39]
	v_lshlrev_b32_e32 v38, 16, v166
	v_mul_f32_e32 v23, 0xbfb8aa3b, v38
	v_exp_f32_e32 v23, v23
	v_pk_mul_f32 v[20:21], v[20:21], s[10:11] op_sel_hi:[1,0]
	v_and_b32_e32 v39, 0xffff0000, v166
	v_fma_f32 v22, -v20, v20, v21
	v_max_f32_e32 v22, 0, v22
	v_add_f32_e32 v23, 1.0, v23
	v_add_f32_e32 v22, 0x3a27c5ac, v22
	v_rcp_f32_e32 v42, v23
	v_mul_f32_e32 v23, 0xbfb8aa3b, v39
	v_rsq_f32_e32 v22, v22
	v_exp_f32_e32 v23, v23
	v_and_b32_e32 v37, 0xffff0000, v168
	v_pk_add_f32 v[54:55], v[54:55], v[20:21] op_sel_hi:[1,0] neg_lo:[0,1] neg_hi:[0,1]
	v_pk_add_f32 v[40:41], v[40:41], v[36:37] neg_lo:[0,1] neg_hi:[0,1]
	v_pk_mul_f32 v[54:55], v[54:55], v[22:23] op_sel_hi:[1,0]
	v_add_f32_e32 v23, 1.0, v23
	v_pk_fma_f32 v[36:37], v[40:41], v[232:233], v[36:37]
	v_lshlrev_b32_e32 v40, 16, v167
	v_rcp_f32_e32 v43, v23
	v_mul_f32_e32 v23, 0xbfb8aa3b, v40
	v_exp_f32_e32 v23, v23
	v_pk_fma_f32 v[54:55], v[228:229], v[54:55], v[250:251]
	v_and_b32_e32 v41, 0xffff0000, v167
	v_pk_fma_f32 v[36:37], v[162:163], v[36:37], v[54:55] op_sel_hi:[0,1,1]
	v_add_f32_e32 v23, 1.0, v23
	v_rcp_f32_e32 v54, v23
	v_mul_f32_e32 v23, 0xbfb8aa3b, v41
	v_exp_f32_e32 v23, v23
	v_pk_add_f32 v[20:21], v[52:53], v[20:21] op_sel_hi:[1,0] neg_lo:[0,1] neg_hi:[0,1]
	v_pk_mul_f32 v[38:39], v[42:43], v[38:39]
	v_lshlrev_b32_e32 v42, 16, v165
	v_pk_mul_f32 v[20:21], v[20:21], v[22:23] op_sel_hi:[1,0]
	v_add_f32_e32 v22, 1.0, v23
	v_rcp_f32_e32 v55, v22
	v_pk_mul_f32 v[36:37], v[38:39], v[36:37]
	v_lshlrev_b32_e32 v38, 16, v169
	v_and_b32_e32 v39, 0xffff0000, v169
	v_and_b32_e32 v43, 0xffff0000, v165
	v_pk_add_f32 v[22:23], v[42:43], v[38:39] neg_lo:[0,1] neg_hi:[0,1]
	v_pk_fma_f32 v[20:21], v[230:231], v[20:21], v[252:253]
	v_pk_fma_f32 v[22:23], v[22:23], v[254:255], v[38:39]
	v_pk_fma_f32 v[20:21], v[162:163], v[22:23], v[20:21] op_sel_hi:[0,1,1]
	v_pk_mul_f32 v[22:23], v[54:55], v[40:41]
	v_pk_mul_f32 v[20:21], v[22:23], v[20:21]
	v_cvt_pk_bf16_f32 v22, v36, v37
	v_cvt_pk_bf16_f32 v23, v20, v21
	v_lshl_add_u64 v[20:21], v[158:159], 0, s[20:21]
	s_add_u32 s20, s20, 0x20000
	global_store_dwordx2 v[20:21], v[22:23], off
	s_addc_u32 s21, s21, 0
	s_add_i32 s39, s39, 1
	s_waitcnt vmcnt(2)
	v_mov_b64_e32 v[58:59], v[46:47]
	v_mov_b64_e32 v[164:165], v[192:193]
	v_mov_b64_e32 v[54:55], v[50:51]
	v_mov_b64_e32 v[38:39], v[26:27]
	v_mov_b64_e32 v[20:21], v[28:29]
	s_cmp_eq_u32 s20, 0x400000
	v_mov_b64_e32 v[170:171], v[186:187]
	v_mov_b64_e32 v[166:167], v[190:191]
	v_mov_b64_e32 v[176:177], v[184:185]
	v_mov_b64_e32 v[174:175], v[182:183]
	v_mov_b64_e32 v[168:169], v[188:189]
	v_mov_b32_e32 v162, v127
	v_mov_b32_e32 v172, v125
	v_mov_b64_e32 v[56:57], v[44:45]
	v_mov_b64_e32 v[52:53], v[48:49]
	v_mov_b64_e32 v[36:37], v[24:25]
	v_mov_b64_e32 v[22:23], v[30:31]
	v_mov_b32_e32 v40, v216
	v_mov_b32_e32 v41, v217
	v_mov_b32_e32 v42, v218
	v_mov_b32_e32 v43, v219
	v_mov_b32_e32 v196, v178
	v_mov_b32_e32 v197, v179
	v_mov_b32_e32 v194, v180
	v_mov_b32_e32 v195, v181
	s_cbranch_scc1 .LBB0_268
.LBB0_280:
	s_cmp_lg_u32 s20, 0x3e0000
	s_cselect_b32 s15, s39, 31
	s_add_u32 s22, s18, s15
	s_addc_u32 s23, s19, 0
	s_mul_i32 s40, s23, 0x6000
	s_mul_hi_u32 s41, s22, 0x6000
	s_add_i32 s41, s41, s40
	s_mul_i32 s40, s22, 0x6000
	s_add_u32 s40, s86, s40
	s_addc_u32 s41, s87, s41
	s_waitcnt vmcnt(12)
	ds_write_b64 v242, v[182:183]
	ds_write_b64 v242, v[188:189] offset:576
	ds_write_b64 v242, v[184:185] offset:9216
	ds_write_b64 v242, v[190:191] offset:9792
	v_mov_b64_e32 v[226:227], v[10:11]
	v_mov_b64_e32 v[224:225], v[8:9]
	s_lshl_b64 s[100:101], s[22:23], 14
	s_add_u32 s100, s3, s100
	s_addc_u32 s101, s11, s101
	s_lshl_b64 s[22:23], s[22:23], 8
	s_add_u32 s22, s24, s22
	s_addc_u32 s23, s25, s23
	v_mov_b64_e32 v[74:75], v[6:7]
	s_lshl_b32 s15, s15, 6
	v_mov_b64_e32 v[72:73], v[4:5]
	v_mov_b64_e32 v[200:201], v[2:3]
	s_waitcnt vmcnt(11)
	v_mov_b64_e32 v[222:223], v[14:15]
	s_add_u32 s15, s16, s15
	v_mov_b64_e32 v[198:199], v[0:1]
	v_mov_b64_e32 v[220:221], v[12:13]
	v_mov_b32_e32 v76, v210
	v_mov_b32_e32 v77, v211
	v_mov_b32_e32 v78, v212
	v_mov_b32_e32 v79, v213
	s_sub_u32 s98, s15, 1
	s_mul_i32 s98, s98, 0x1c00
	s_add_u32 s98, s98, s94
	s_addc_u32 s99, s95, 0
	s_mov_b32 vcc_lo, 0x10001
	s_mov_b32 vcc_hi, 0x10001
	global_load_dwordx2 v[182:183], v240, s[98:99]
	global_load_dwordx2 v[188:189], v241, s[98:99]
	global_load_dwordx2 v[184:185], v240, s[98:99] offset:1280
	global_load_dwordx2 v[190:191], v241, s[98:99] offset:1280
	s_mov_b64 exec, vcc
	global_load_dwordx2 v[186:187], v245, s[98:99]
	s_mov_b64 exec, -1
	global_load_dword v125, v214, s[22:23]
	global_load_dword v127, v215, s[22:23]
	v_cvt_pk_bf16_f32 v80, v16, 0
	v_lshlrev_b32_e32 v81, 16, v80
	v_sub_f32_e32 v16, v16, v81
	v_cvt_pk_bf16_f32 v16, v16, s0
	ds_write_b16 v107, v80
	ds_write_b16 v107, v16 offset:9216
	v_cvt_pk_bf16_f32 v16, v17, 0
	v_lshlrev_b32_e32 v80, 16, v16
	v_sub_f32_e32 v17, v17, v80
	v_cvt_pk_bf16_f32 v17, v17, s0
	ds_write_b16 v107, v16 offset:144
	ds_write_b16 v107, v17 offset:9360
	v_cvt_pk_bf16_f32 v16, v18, 0
	v_lshlrev_b32_e32 v17, 16, v16
	v_sub_f32_e32 v17, v18, v17
	v_cvt_pk_bf16_f32 v17, v17, s0
	ds_write_b16 v107, v16 offset:288
	ds_write_b16 v107, v17 offset:9504
	v_cvt_pk_bf16_f32 v16, v19, 0
	v_lshlrev_b32_e32 v17, 16, v16
	v_sub_f32_e32 v17, v19, v17
	v_cvt_pk_bf16_f32 v17, v17, s0
	ds_write_b16 v107, v16 offset:432
	ds_write_b16 v107, v17 offset:9648
	v_cvt_pk_bf16_f32 v16, v32, 0
	v_lshlrev_b32_e32 v17, 16, v16
	v_sub_f32_e32 v17, v32, v17
	v_cvt_pk_bf16_f32 v17, v17, s0
	ds_write_b16 v135, v16
	ds_write_b16 v135, v17 offset:9216
	v_cvt_pk_bf16_f32 v16, v33, 0
	v_lshlrev_b32_e32 v17, 16, v16
	v_sub_f32_e32 v17, v33, v17
	v_cvt_pk_bf16_f32 v17, v17, s0
	ds_write_b16 v135, v16 offset:144
	ds_write_b16 v135, v17 offset:9360
	v_cvt_pk_bf16_f32 v16, v34, 0
	v_lshlrev_b32_e32 v17, 16, v16
	v_sub_f32_e32 v17, v34, v17
	v_cvt_pk_bf16_f32 v17, v17, s0
	ds_write_b16 v135, v16 offset:288
	ds_write_b16 v135, v17 offset:9504
	v_cvt_pk_bf16_f32 v16, v35, 0
	v_lshlrev_b32_e32 v17, 16, v16
	v_sub_f32_e32 v17, v35, v17
	v_cvt_pk_bf16_f32 v17, v17, s0
	ds_write_b16 v135, v16 offset:432
	ds_write_b16 v135, v17 offset:9648
	s_waitcnt lgkmcnt(0)
	s_barrier
	ds_read_b128 v[80:83], v139
	ds_read_b128 v[32:35], v139 offset:64
	s_waitcnt lgkmcnt(1)
	v_mfma_f32_16x16x32_bf16 v[16:19], v[80:83], v[198:201], v[76:79]
	ds_read_b128 v[84:87], v139 offset:9216
	s_nop 1
	ds_read_b128 v[76:79], v139 offset:9280
	s_waitcnt vmcnt(7)
	v_lshlrev_b32_e32 v202, 16, v196
	v_and_b32_e32 v203, 0xffff0000, v196
	s_waitcnt lgkmcnt(1)
	v_mfma_f32_16x16x32_bf16 v[16:19], v[84:87], v[198:201], v[16:19]
	v_lshlrev_b32_e32 v196, 16, v197
	v_and_b32_e32 v197, 0xffff0000, v197
	v_and_b32_e32 v151, 64, v209
	v_mfma_f32_16x16x32_bf16 v[198:201], v[80:83], v[224:227], 0
	v_xor_b32_e32 v149, 16, v209
	v_add_u32_e32 v151, 64, v151
	v_cmp_lt_i32_e32 vcc, v149, v151
	v_mfma_f32_16x16x32_bf16 v[198:201], v[32:35], v[220:223], v[198:201]
	v_xor_b32_e32 v224, 32, v209
	v_cndmask_b32_e32 v149, v209, v149, vcc
	v_lshlrev_b32_e32 v149, 2, v149
	v_cmp_lt_i32_e32 vcc, v224, v151
	v_mfma_f32_16x16x32_bf16 v[16:19], v[32:35], v[72:75], v[16:19]
	global_load_dwordx4 v[0:3], v234, s[40:41]
	global_load_dwordx4 v[4:7], v234, s[40:41] offset:1024
	s_nop 2
	v_add_f32_e64 v198, v198, v202
	v_add_f32_e64 v199, v199, v203
	v_pk_add_f32 v[196:197], v[200:201], v[196:197]
	v_pk_mul_f32 v[200:201], v[198:199], v[198:199]
	v_pk_mul_f32 v[202:203], v[196:197], v[196:197]
	global_load_dwordx4 v[24:27], v235, s[40:41]
	v_mov_b32_e32 v220, v198
	v_mov_b32_e32 v221, v200
	v_mov_b32_e32 v200, v199
	v_pk_add_f32 v[200:201], v[220:221], v[200:201]
	global_load_dwordx4 v[28:31], v235, s[40:41] offset:1024
	v_mov_b32_e32 v220, v196
	v_mov_b32_e32 v221, v202
	v_mov_b32_e32 v202, v197
	v_pk_add_f32 v[202:203], v[220:221], v[202:203]
	v_cndmask_b32_e32 v151, v209, v224, vcc
	global_load_dwordx4 v[210:213], v236, s[40:41]
	v_pk_add_f32 v[200:201], v[200:201], v[202:203]
	ds_bpermute_b32 v202, v149, v200
	ds_bpermute_b32 v203, v149, v201
	v_lshlrev_b32_e32 v151, 2, v151
	global_load_dwordx4 v[216:219], v237, s[40:41]
	s_waitcnt lgkmcnt(2)
	v_mfma_f32_16x16x32_bf16 v[16:19], v[76:79], v[72:75], v[16:19]
	s_waitcnt lgkmcnt(0)
	v_pk_add_f32 v[200:201], v[200:201], v[202:203]
	ds_bpermute_b32 v202, v151, v200
	ds_bpermute_b32 v203, v151, v201
	s_and_saveexec_b64 s[22:23], s[30:31]
	s_cbranch_execz .LBB0_282
	s_waitcnt lgkmcnt(0)
	v_pk_add_f32 v[72:73], v[200:201], v[202:203]
	v_add_u32_e32 v74, s26, v130
	ds_write_b64 v74, v[72:73] offset:18432
.LBB0_282:
	s_or_b64 exec, exec, s[22:23]
	s_waitcnt vmcnt(13)
	v_mfma_f32_16x16x32_bf16 v[56:59], v[80:83], v[56:59], 0
	s_waitcnt vmcnt(13)
	v_lshlrev_b32_e32 v72, 16, v194
	v_and_b32_e32 v73, 0xffff0000, v194
	v_lshlrev_b32_e32 v74, 16, v195
	v_mfma_f32_16x16x32_bf16 v[54:57], v[32:35], v[52:55], v[56:59]
	v_and_b32_e32 v75, 0xffff0000, v195
	v_mfma_f32_16x16x32_bf16 v[40:43], v[80:83], v[36:39], v[40:43]
	v_mfma_f32_16x16x32_bf16 v[36:39], v[84:87], v[36:39], v[40:43]
	s_nop 4
	v_add_f32_e64 v54, v54, v72
	v_add_f32_e64 v55, v55, v73
	v_pk_add_f32 v[52:53], v[56:57], v[74:75]
	v_pk_mul_f32 v[56:57], v[54:55], v[54:55]
	v_pk_mul_f32 v[58:59], v[52:53], v[52:53]
	v_mov_b32_e32 v72, v54
	v_mov_b32_e32 v73, v56
	v_mov_b32_e32 v56, v55
	v_mov_b32_e32 v42, v52
	v_mov_b32_e32 v43, v58
	v_mov_b32_e32 v58, v53
	v_pk_add_f32 v[40:41], v[72:73], v[56:57]
	v_pk_add_f32 v[42:43], v[42:43], v[58:59]
	v_mfma_f32_16x16x32_bf16 v[32:35], v[32:35], v[20:23], v[36:39]
	v_add_f32_e64 v40, v40, v42
	v_add_f32_e64 v41, v41, v43
	ds_bpermute_b32 v42, v149, v40
	ds_bpermute_b32 v43, v149, v41
	v_mfma_f32_16x16x32_bf16 v[32:35], v[76:79], v[20:23], v[32:35]
	s_waitcnt lgkmcnt(0)
	v_pk_add_f32 v[36:37], v[40:41], v[42:43]
	ds_bpermute_b32 v38, v151, v36
	ds_bpermute_b32 v39, v151, v37
	ds_read_b64 v[174:175], v243
	ds_read_b64 v[168:169], v243 offset:2304
	ds_read_b64 v[176:177], v243 offset:9216
	ds_read_b64 v[166:167], v243 offset:11520
	s_and_saveexec_b64 s[22:23], s[30:31]
	s_cbranch_execz .LBB0_279
	s_waitcnt lgkmcnt(0)
	v_pk_add_f32 v[20:21], v[36:37], v[38:39]
	v_add_u32_e32 v22, s27, v130
	ds_write_b64 v22, v[20:21] offset:18432
	s_branch .LBB0_279
